# SEL compaction rewritten: 8 keys per lane per LDS read, per-lane bitmasks, DPP prefix scan, ffs emit loops; leaner score loop (permlane32_swap instead of bpermute)
# speedup vs baseline: 1.0381x; 1.0381x over previous
; DI void select_item(const P& p, int b, int quad4, int bid, char* smem, const SelPre& pre) {
;     ...
;   {
;     const int r = lane & 31, h = lane >> 5;
;     bf16x8 a[4];
;     float4 w[4];
; #pragma unroll
;     for (int s = 0; s < 4; ++s) { a[s] = pre.a[s]; w[s] = pre.w[s]; }
;     const int ntile = (t0 + 4 + 31) >> 5;
;     const bf16_t* kbase = p.kidx + ((size_t)b * SEQ) * 64 + h * 8;
;     const int nit = (ntile - wave + 3) >> 2;
; #pragma unroll 1
;     for (int i0 = 0; i0 < nit; i0 += 4) {
;       bf16x8 bf[4][4];
; #pragma unroll
;       for (int u = 0; u < 4; ++u) {
;         int kt = wave + 4 * (i0 + u); kt = kt < ntile ? kt : ntile - 1;
;         const bf16_t* kp = kbase + (size_t)(kt * 32 + r) * 64;
; #pragma unroll
;         for (int s = 0; s < 4; ++s) bf[u][s] = *(const bf16x8*)(kp + s * 16);
;       }
; #pragma unroll
;       for (int u = 0; u < 4; ++u) {
;         const int key = (wave + 4 * (i0 + u)) * 32 + r;
;         f32x16 acc;
; #pragma unroll
;         for (int i = 0; i < 16; ++i) acc[i] = 0.f;
; #pragma unroll
;         for (int s = 0; s < 4; ++s) acc = __builtin_amdgcn_mfma_f32_32x32x16_bf16(a[s], bf[u][s], acc, 0, 0, 0);
.LBB0_448:
	s_lshl_b32 s0, s0, 2
	s_sub_i32 s30, 0x1ffc, s0
	s_cmpk_lt_u32 s30, 0x100
	s_cbranch_scc1 .LBB0_444
	v_mov_b32_e32 v8, v218
	s_sub_i32 s0, 0x201c, s0
	s_lshr_b32 s10, s0, 5
	v_ashrrev_i32_e32 v122, 6, v8
	v_sub_u32_e32 v9, s10, v122
	v_add_u32_e32 v9, 3, v9
	v_ashrrev_i32_e32 v121, 2, v9
	v_cmp_gt_i32_e32 vcc, 1, v121
	s_waitcnt lgkmcnt(0)
	s_barrier
	s_and_saveexec_b64 s[0:1], vcc
	s_xor_b64 s[0:1], exec, s[0:1]
	v_mbcnt_hi_u32_b32 v14, -1, v222
	s_or_saveexec_b64 s[4:5], s[0:1]
	v_and_b32_e32 v120, 63, v8
	s_xor_b64 exec, exec, s[4:5]
	s_cbranch_execz .LBB0_461
	v_and_b32_e32 v123, 31, v8
	v_lshrrev_b32_e32 v8, 5, v120
	v_readlane_b32 s0, v250, 33
	v_lshlrev_b32_e32 v192, 4, v8
	v_readlane_b32 s1, v250, 34
	v_and_b32_e32 v10, 64, v223
	s_waitcnt vmcnt(0)
	v_mov_b32_e32 v136, v65
	v_lshl_add_u64 v[124:125], s[0:1], 0, v[192:193]
	v_readlane_b32 s0, v250, 21
	v_lshlrev_b32_e32 v192, 16, v8
	v_readlane_b32 s1, v250, 22
	v_mov_b32_e32 v65, v0
	v_lshlrev_b32_e32 v0, 6, v122
	v_xor_b32_e32 v9, 32, v223
	v_add_u32_e32 v10, 64, v10
	v_lshl_add_u64 v[126:127], s[0:1], 0, v[192:193]
	v_or_b32_e32 v192, 0x8000, v192
	v_lshl_add_u32 v0, v8, 15, v0
	v_cmp_lt_i32_e32 vcc, v9, v10
	v_lshl_add_u64 v[128:129], s[0:1], 0, v[192:193]
	v_lshl_or_b32 v0, v123, 1, v0
	v_readlane_b32 s0, v249, 18
	v_cndmask_b32_e32 v9, v223, v9, vcc
	s_add_i32 s10, s10, -1
	v_add_u32_e32 v141, s0, v0
	v_lshl_or_b32 v0, v122, 5, v123
	s_mov_b32 s11, 0
	v_lshlrev_b32_e32 v140, 2, v9
	v_cmp_gt_u32_e32 vcc, 32, v120
	v_mov_b32_e32 v130, v71
	v_mov_b32_e32 v131, v7
	v_mov_b32_e32 v71, v6
	v_mov_b32_e32 v132, v69
	v_mov_b32_e32 v133, v5
	v_mov_b32_e32 v69, v4
	v_mov_b32_e32 v134, v67
	v_mov_b32_e32 v135, v3
	v_mov_b32_e32 v67, v2
	v_mov_b32_e32 v137, v1
	v_add_u32_e32 v138, 0x180, v0
	s_mov_b64 s[6:7], 0
	v_mov_b32_e32 v142, v122
	v_readfirstlane_b32 s8, v121
	v_lshrrev_b32_e32 v246, 5, v120
	v_mul_u32_u24_e32 v246, 0x1f0, v246
	v_lshl_add_u32 v246, v123, 4, v246
	v_mov_b32_e32 v247, 0
	v_lshl_add_u64 v[244:245], v[124:125], 0, v[246:247]
	v_mov_b32_e32 v236, v142
	v_min_i32_e32 v236, s10, v236
	v_lshlrev_b32_e32 v236, 12, v236
	v_mov_b32_e32 v237, 0
	v_lshl_add_u64 v[236:237], v[244:245], 0, v[236:237]
	v_add_u32_e32 v238, 4, v142
	v_min_i32_e32 v238, s10, v238
	v_lshlrev_b32_e32 v238, 12, v238
	v_mov_b32_e32 v239, 0
	v_lshl_add_u64 v[238:239], v[244:245], 0, v[238:239]
	global_load_dwordx4 v[160:163], v[236:237], off
	global_load_dwordx4 v[176:179], v[238:239], off
	global_load_dwordx4 v[164:167], v[236:237], off offset:1024
	global_load_dwordx4 v[180:183], v[238:239], off offset:1024
	global_load_dwordx4 v[168:171], v[236:237], off offset:2048
	global_load_dwordx4 v[184:187], v[238:239], off offset:2048
	global_load_dwordx4 v[172:175], v[236:237], off offset:3072
	global_load_dwordx4 v[188:191], v[238:239], off offset:3072
	v_add_u32_e32 v236, 8, v142
	v_min_i32_e32 v236, s10, v236
	v_lshlrev_b32_e32 v236, 12, v236
	v_mov_b32_e32 v237, 0
	v_lshl_add_u64 v[236:237], v[244:245], 0, v[236:237]
	global_load_dwordx4 v[194:197], v[236:237], off
	global_load_dwordx4 v[198:201], v[236:237], off offset:1024
	global_load_dwordx4 v[202:205], v[236:237], off offset:2048
	global_load_dwordx4 v[206:209], v[236:237], off offset:3072
	v_add_u32_e32 v238, 12, v142
	v_min_i32_e32 v238, s10, v238
	v_lshlrev_b32_e32 v238, 12, v238
	v_mov_b32_e32 v239, 0
	v_lshl_add_u64 v[238:239], v[244:245], 0, v[238:239]
	global_load_dwordx4 v[210:213], v[238:239], off
	global_load_dwordx4 v[214:217], v[238:239], off offset:1024
	global_load_dwordx4 v[228:231], v[238:239], off offset:2048
	global_load_dwordx4 v[232:235], v[238:239], off offset:3072
	s_waitcnt vmcnt(0)
	s_branch .LBB0_454
.LBB0_453:
.Lsc_latch:
	s_add_i32 s11, s11, 4
	v_cmp_ge_i32_e64 s[0:1], s11, v121
	v_add_u32_e32 v141, 0x400, v141
	v_add_u32_e32 v138, 0x200, v138
	s_or_b64 s[6:7], s[0:1], s[6:7]
	v_add_u32_e32 v142, 16, v142
	s_andn2_b64 exec, exec, s[6:7]
	s_cbranch_execz .LBB0_460
.LBB0_454:
	s_waitcnt vmcnt(17)
	v_mfma_f32_32x32x16_bf16 v[0:15], v[84:87], v[160:163], 0
	s_waitcnt vmcnt(16)
	v_mfma_f32_32x32x16_bf16 v[16:31], v[84:87], v[176:179], 0
	s_waitcnt vmcnt(15)
	v_mfma_f32_32x32x16_bf16 v[0:15], v[80:83], v[164:167], v[0:15]
	s_waitcnt vmcnt(14)
	v_mfma_f32_32x32x16_bf16 v[16:31], v[80:83], v[180:183], v[16:31]
	s_waitcnt vmcnt(13)
	v_mfma_f32_32x32x16_bf16 v[0:15], v[76:79], v[168:171], v[0:15]
	s_waitcnt vmcnt(12)
	v_mfma_f32_32x32x16_bf16 v[16:31], v[76:79], v[184:187], v[16:31]
	s_waitcnt vmcnt(11)
	v_mfma_f32_32x32x16_bf16 v[0:15], v[72:75], v[172:175], v[0:15]
	s_waitcnt vmcnt(10)
; DI unsigned mono(float f) { const unsigned u = __float_as_uint(f); return (u & 0x80000000u) ? ~u : (u | 0x80000000u); }
; DI void select_item(const P& p, int b, int quad4, int bid, char* smem, const SelPre& pre) {
;     ...
;       for (int u = 0; u < 4; ++u) {
;         const int key = (wave + 4 * (i0 + u)) * 32 + r;
;         f32x16 acc;
; #pragma unroll
;         for (int i = 0; i < 16; ++i) acc[i] = 0.f;
; #pragma unroll
;         for (int s = 0; s < 4; ++s) acc = __builtin_amdgcn_mfma_f32_32x32x16_bf16(a[s], bf[u][s], acc, 0, 0, 0);
;         float tot[4];
; #pragma unroll
;         for (int q = 0; q < 4; ++q) {
;           float sq = 0.f;
;           sq = fmaf(fmaxf(acc[4 * q + 0], 0.f), w[q].x, sq); sq = fmaf(fmaxf(acc[4 * q + 1], 0.f), w[q].y, sq);
;           sq = fmaf(fmaxf(acc[4 * q + 2], 0.f), w[q].z, sq); sq = fmaf(fmaxf(acc[4 * q + 3], 0.f), w[q].w, sq);
;           tot[q] = sq + __shfl_xor(sq, 32);
;         }
;         if (i0 + u < nit) {
;           const unsigned m0 = mono(h == 0 ? tot[0] : tot[2]), m1 = mono(h == 0 ? tot[1] : tot[3]);
;           const int q0 = h * 2;
;           sc16[q0 * 8192 + key] = (unsigned short)(m0 >> 16); sc16[(q0 + 1) * 8192 + key] = (unsigned short)(m1 >> 16);
;           __builtin_nontemporal_store(m0, scr + q0 * 8192 + key); __builtin_nontemporal_store(m1, scr + (q0 + 1) * 8192 + key);
;         }
	v_mfma_f32_32x32x16_bf16 v[16:31], v[72:75], v[188:191], v[16:31]
	v_add_u32_e32 v236, 16, v142
	v_min_i32_e32 v236, s10, v236
	v_lshlrev_b32_e32 v236, 12, v236
	v_mov_b32_e32 v237, 0
	v_lshl_add_u64 v[236:237], v[244:245], 0, v[236:237]
	v_add_u32_e32 v238, 20, v142
	v_min_i32_e32 v238, s10, v238
	v_lshlrev_b32_e32 v238, 12, v238
	v_mov_b32_e32 v239, 0
	v_lshl_add_u64 v[238:239], v[244:245], 0, v[238:239]
	global_load_dwordx4 v[160:163], v[236:237], off
	global_load_dwordx4 v[176:179], v[238:239], off
	global_load_dwordx4 v[164:167], v[236:237], off offset:1024
	global_load_dwordx4 v[180:183], v[238:239], off offset:1024
	global_load_dwordx4 v[168:171], v[236:237], off offset:2048
	global_load_dwordx4 v[184:187], v[238:239], off offset:2048
	global_load_dwordx4 v[172:175], v[236:237], off offset:3072
	global_load_dwordx4 v[188:191], v[238:239], off offset:3072
	v_max_f32_e32 v145, 0, v0
	v_max_f32_e32 v144, 0, v4
	v_max_f32_e32 v147, 0, v1
	v_max_f32_e32 v146, 0, v5
	v_max_f32_e32 v149, 0, v2
	v_max_f32_e32 v148, 0, v6
	v_max_f32_e32 v151, 0, v3
	v_max_f32_e32 v150, 0, v7
	v_max_f32_e32 v153, 0, v8
	v_max_f32_e32 v152, 0, v12
	v_max_f32_e32 v155, 0, v9
	v_max_f32_e32 v154, 0, v13
	v_max_f32_e32 v157, 0, v10
	v_max_f32_e32 v156, 0, v14
	v_max_f32_e32 v159, 0, v11
	v_max_f32_e32 v158, 0, v15
	v_pk_fma_f32 v[144:145], v[144:145], v[68:69], 0 op_sel_hi:[1,1,0]
	v_pk_fma_f32 v[152:153], v[152:153], v[64:65], 0 op_sel_hi:[1,1,0]
	v_pk_fma_f32 v[144:145], v[146:147], v[132:133], v[144:145]
	v_pk_fma_f32 v[152:153], v[154:155], v[136:137], v[152:153]
	v_pk_fma_f32 v[144:145], v[148:149], v[70:71], v[144:145]
	v_pk_fma_f32 v[152:153], v[156:157], v[66:67], v[152:153]
	v_pk_fma_f32 v[144:145], v[150:151], v[130:131], v[144:145]
	v_pk_fma_f32 v[152:153], v[158:159], v[134:135], v[152:153]
	v_add_u32_e32 v240, 0xfffffe80, v138
	v_ashrrev_i32_e32 v241, 31, v240
	v_lshlrev_b64 v[240:241], 2, v[240:241]
	v_permlane32_swap_b32_e32 v145, v153
	v_permlane32_swap_b32_e32 v144, v152
	v_lshl_add_u64 v[242:243], v[126:127], 0, v[240:241]
	v_lshl_add_u64 v[240:241], v[128:129], 0, v[240:241]
	v_pk_add_f32 v[144:145], v[144:145], v[152:153]
	s_nop 0
	v_ashrrev_i32_e32 v146, 31, v145
	v_ashrrev_i32_e32 v147, 31, v144
	v_or_b32_e32 v146, 0x80000000, v146
	v_or_b32_e32 v147, 0x80000000, v147
	v_xor_b32_e32 v145, v145, v146
	v_xor_b32_e32 v144, v144, v147
	ds_write_b16_d16_hi v141, v145
	ds_write_b16_d16_hi v141, v144 offset:16384
	global_store_dword v[242:243], v145, off nt
	global_store_dword v[240:241], v144, off nt
	v_max_f32_e32 v145, 0, v16
	v_max_f32_e32 v144, 0, v20
	v_max_f32_e32 v147, 0, v17
	v_max_f32_e32 v146, 0, v21
	v_max_f32_e32 v149, 0, v18
	v_max_f32_e32 v148, 0, v22
	v_max_f32_e32 v151, 0, v19
	v_max_f32_e32 v150, 0, v23
	v_max_f32_e32 v153, 0, v24
	v_max_f32_e32 v152, 0, v28
	v_max_f32_e32 v155, 0, v25
	v_max_f32_e32 v154, 0, v29
	v_max_f32_e32 v157, 0, v26
	v_max_f32_e32 v156, 0, v30
	v_max_f32_e32 v159, 0, v27
	v_max_f32_e32 v158, 0, v31
	v_pk_fma_f32 v[144:145], v[144:145], v[68:69], 0 op_sel_hi:[1,1,0]
	v_pk_fma_f32 v[152:153], v[152:153], v[64:65], 0 op_sel_hi:[1,1,0]
	v_pk_fma_f32 v[144:145], v[146:147], v[132:133], v[144:145]
	v_pk_fma_f32 v[152:153], v[154:155], v[136:137], v[152:153]
	v_pk_fma_f32 v[144:145], v[148:149], v[70:71], v[144:145]
	v_pk_fma_f32 v[152:153], v[156:157], v[66:67], v[152:153]
	v_pk_fma_f32 v[144:145], v[150:151], v[130:131], v[144:145]
	v_pk_fma_f32 v[152:153], v[158:159], v[134:135], v[152:153]
	v_add_u32_e32 v240, 0xffffff00, v138
	v_ashrrev_i32_e32 v241, 31, v240
	v_lshlrev_b64 v[240:241], 2, v[240:241]
	v_permlane32_swap_b32_e32 v145, v153
	v_permlane32_swap_b32_e32 v144, v152
	v_lshl_add_u64 v[242:243], v[126:127], 0, v[240:241]
	v_lshl_add_u64 v[240:241], v[128:129], 0, v[240:241]
	v_pk_add_f32 v[144:145], v[144:145], v[152:153]
	s_nop 0
	v_ashrrev_i32_e32 v146, 31, v145
	v_ashrrev_i32_e32 v147, 31, v144
	v_or_b32_e32 v146, 0x80000000, v146
	v_or_b32_e32 v147, 0x80000000, v147
	v_xor_b32_e32 v145, v145, v146
	v_xor_b32_e32 v144, v144, v147
	s_add_i32 s9, s11, 1
	s_cmp_lt_i32 s9, s8
	s_cbranch_scc0 .Lsc_skip1
	ds_write_b16_d16_hi v141, v145 offset:256
	ds_write_b16_d16_hi v141, v144 offset:16640
	global_store_dword v[242:243], v145, off nt
	global_store_dword v[240:241], v144, off nt
; DI unsigned mono(float f) { const unsigned u = __float_as_uint(f); return (u & 0x80000000u) ? ~u : (u | 0x80000000u); }
; DI void select_item(const P& p, int b, int quad4, int bid, char* smem, const SelPre& pre) {
;     ...
;       for (int u = 0; u < 4; ++u) {
;         const int key = (wave + 4 * (i0 + u)) * 32 + r;
;         f32x16 acc;
; #pragma unroll
;         for (int i = 0; i < 16; ++i) acc[i] = 0.f;
; #pragma unroll
;         for (int s = 0; s < 4; ++s) acc = __builtin_amdgcn_mfma_f32_32x32x16_bf16(a[s], bf[u][s], acc, 0, 0, 0);
;         float tot[4];
; #pragma unroll
;         for (int q = 0; q < 4; ++q) {
;           float sq = 0.f;
;           sq = fmaf(fmaxf(acc[4 * q + 0], 0.f), w[q].x, sq); sq = fmaf(fmaxf(acc[4 * q + 1], 0.f), w[q].y, sq);
;           sq = fmaf(fmaxf(acc[4 * q + 2], 0.f), w[q].z, sq); sq = fmaf(fmaxf(acc[4 * q + 3], 0.f), w[q].w, sq);
;           tot[q] = sq + __shfl_xor(sq, 32);
;         }
;         if (i0 + u < nit) {
;           const unsigned m0 = mono(h == 0 ? tot[0] : tot[2]), m1 = mono(h == 0 ? tot[1] : tot[3]);
;           const int q0 = h * 2;
;           sc16[q0 * 8192 + key] = (unsigned short)(m0 >> 16); sc16[(q0 + 1) * 8192 + key] = (unsigned short)(m1 >> 16);
;           __builtin_nontemporal_store(m0, scr + q0 * 8192 + key); __builtin_nontemporal_store(m1, scr + (q0 + 1) * 8192 + key);
;         }
.Lsc_skip1:
	s_waitcnt vmcnt(17)
	v_mfma_f32_32x32x16_bf16 v[0:15], v[84:87], v[194:197], 0
	s_waitcnt vmcnt(16)
	v_mfma_f32_32x32x16_bf16 v[0:15], v[80:83], v[198:201], v[0:15]
	s_waitcnt vmcnt(15)
	v_mfma_f32_32x32x16_bf16 v[0:15], v[76:79], v[202:205], v[0:15]
	s_waitcnt vmcnt(14)
	v_mfma_f32_32x32x16_bf16 v[0:15], v[72:75], v[206:209], v[0:15]
	v_add_u32_e32 v236, 24, v142
	v_min_i32_e32 v236, s10, v236
	v_lshlrev_b32_e32 v236, 12, v236
	v_mov_b32_e32 v237, 0
	v_lshl_add_u64 v[236:237], v[244:245], 0, v[236:237]
	global_load_dwordx4 v[194:197], v[236:237], off
	global_load_dwordx4 v[198:201], v[236:237], off offset:1024
	global_load_dwordx4 v[202:205], v[236:237], off offset:2048
	global_load_dwordx4 v[206:209], v[236:237], off offset:3072
	s_nop 4
	v_max_f32_e32 v145, 0, v0
	v_max_f32_e32 v144, 0, v4
	v_max_f32_e32 v147, 0, v1
	v_max_f32_e32 v146, 0, v5
	v_max_f32_e32 v149, 0, v2
	v_max_f32_e32 v148, 0, v6
	v_max_f32_e32 v151, 0, v3
	v_max_f32_e32 v150, 0, v7
	v_max_f32_e32 v153, 0, v8
	v_max_f32_e32 v152, 0, v12
	v_max_f32_e32 v155, 0, v9
	v_max_f32_e32 v154, 0, v13
	v_max_f32_e32 v157, 0, v10
	v_max_f32_e32 v156, 0, v14
	v_max_f32_e32 v159, 0, v11
	v_max_f32_e32 v158, 0, v15
	v_pk_fma_f32 v[144:145], v[144:145], v[68:69], 0 op_sel_hi:[1,1,0]
	v_pk_fma_f32 v[152:153], v[152:153], v[64:65], 0 op_sel_hi:[1,1,0]
	v_pk_fma_f32 v[144:145], v[146:147], v[132:133], v[144:145]
	v_pk_fma_f32 v[152:153], v[154:155], v[136:137], v[152:153]
	v_pk_fma_f32 v[144:145], v[148:149], v[70:71], v[144:145]
	v_pk_fma_f32 v[152:153], v[156:157], v[66:67], v[152:153]
	v_pk_fma_f32 v[144:145], v[150:151], v[130:131], v[144:145]
	v_pk_fma_f32 v[152:153], v[158:159], v[134:135], v[152:153]
	v_add_u32_e32 v240, 0xffffff80, v138
	v_ashrrev_i32_e32 v241, 31, v240
	v_lshlrev_b64 v[240:241], 2, v[240:241]
	v_permlane32_swap_b32_e32 v145, v153
	v_permlane32_swap_b32_e32 v144, v152
	v_lshl_add_u64 v[242:243], v[126:127], 0, v[240:241]
	v_lshl_add_u64 v[240:241], v[128:129], 0, v[240:241]
	v_pk_add_f32 v[144:145], v[144:145], v[152:153]
	s_nop 0
	v_ashrrev_i32_e32 v146, 31, v145
	v_ashrrev_i32_e32 v147, 31, v144
	v_or_b32_e32 v146, 0x80000000, v146
	v_or_b32_e32 v147, 0x80000000, v147
	v_xor_b32_e32 v145, v145, v146
	v_xor_b32_e32 v144, v144, v147
	s_add_i32 s9, s11, 2
	s_cmp_lt_i32 s9, s8
	s_cbranch_scc0 .Lsc_skip2
	ds_write_b16_d16_hi v141, v145 offset:512
	ds_write_b16_d16_hi v141, v144 offset:16896
	global_store_dword v[242:243], v145, off nt
	global_store_dword v[240:241], v144, off nt
.Lsc_skip2:
	s_waitcnt vmcnt(17)
	v_mfma_f32_32x32x16_bf16 v[16:31], v[84:87], v[210:213], 0
	s_waitcnt vmcnt(16)
	v_mfma_f32_32x32x16_bf16 v[16:31], v[80:83], v[214:217], v[16:31]
	s_waitcnt vmcnt(15)
	v_mfma_f32_32x32x16_bf16 v[16:31], v[76:79], v[228:231], v[16:31]
	s_waitcnt vmcnt(14)
	v_mfma_f32_32x32x16_bf16 v[16:31], v[72:75], v[232:235], v[16:31]
	v_add_u32_e32 v238, 28, v142
	v_min_i32_e32 v238, s10, v238
	v_lshlrev_b32_e32 v238, 12, v238
	v_mov_b32_e32 v239, 0
	v_lshl_add_u64 v[238:239], v[244:245], 0, v[238:239]
	global_load_dwordx4 v[210:213], v[238:239], off
	global_load_dwordx4 v[214:217], v[238:239], off offset:1024
	global_load_dwordx4 v[228:231], v[238:239], off offset:2048
	global_load_dwordx4 v[232:235], v[238:239], off offset:3072
	s_nop 4
	v_max_f32_e32 v145, 0, v16
	v_max_f32_e32 v144, 0, v20
	v_max_f32_e32 v147, 0, v17
	v_max_f32_e32 v146, 0, v21
	v_max_f32_e32 v149, 0, v18
	v_max_f32_e32 v148, 0, v22
	v_max_f32_e32 v151, 0, v19
	v_max_f32_e32 v150, 0, v23
	v_max_f32_e32 v153, 0, v24
	v_max_f32_e32 v152, 0, v28
	v_max_f32_e32 v155, 0, v25
	v_max_f32_e32 v154, 0, v29
	v_max_f32_e32 v157, 0, v26
	v_max_f32_e32 v156, 0, v30
	v_max_f32_e32 v159, 0, v27
	v_max_f32_e32 v158, 0, v31
	v_pk_fma_f32 v[144:145], v[144:145], v[68:69], 0 op_sel_hi:[1,1,0]
	v_pk_fma_f32 v[152:153], v[152:153], v[64:65], 0 op_sel_hi:[1,1,0]
	v_pk_fma_f32 v[144:145], v[146:147], v[132:133], v[144:145]
	v_pk_fma_f32 v[152:153], v[154:155], v[136:137], v[152:153]
	v_pk_fma_f32 v[144:145], v[148:149], v[70:71], v[144:145]
	v_pk_fma_f32 v[152:153], v[156:157], v[66:67], v[152:153]
	v_pk_fma_f32 v[144:145], v[150:151], v[130:131], v[144:145]
	v_pk_fma_f32 v[152:153], v[158:159], v[134:135], v[152:153]
	v_mov_b32_e32 v240, v138
	v_ashrrev_i32_e32 v241, 31, v240
	v_lshlrev_b64 v[240:241], 2, v[240:241]
	v_permlane32_swap_b32_e32 v145, v153
	v_permlane32_swap_b32_e32 v144, v152
	v_lshl_add_u64 v[242:243], v[126:127], 0, v[240:241]
	v_lshl_add_u64 v[240:241], v[128:129], 0, v[240:241]
	v_pk_add_f32 v[144:145], v[144:145], v[152:153]
	s_nop 0
	v_ashrrev_i32_e32 v146, 31, v145
	v_ashrrev_i32_e32 v147, 31, v144
	v_or_b32_e32 v146, 0x80000000, v146
	v_or_b32_e32 v147, 0x80000000, v147
	v_xor_b32_e32 v145, v145, v146
	v_xor_b32_e32 v144, v144, v147
	s_add_i32 s9, s11, 3
	s_cmp_lt_i32 s9, s8
	s_cbranch_scc0 .Lsc_latch
	ds_write_b16_d16_hi v141, v145 offset:768
	ds_write_b16_d16_hi v141, v144 offset:17152
	global_store_dword v[242:243], v145, off nt
	global_store_dword v[240:241], v144, off nt
	s_branch .Lsc_latch

; DI void select_item(const P& p, int b, int quad4, int bid, char* smem, const SelPre& pre) {
;     ...
;     const unsigned thr = prefix, ngt = 256 - need;
;     unsigned short* dst = p.sel + (tok0 + qi) * 256;
;     const unsigned long long lm = (1ull << lane) - 1ull;
;     unsigned og = 0, oe = 0;
;     for (int base = 0; base < n; base += 64) {
;       const int e = base + lane;
;       const unsigned u = e < n ? (unsigned)s[e] : 0u;
;       const bool isg = e < n && u > thr, ise = e < n && u == thr;
;       const unsigned long long bg = __ballot(isg), be = __ballot(ise);
;       if (isg) { const unsigned pos = og + __popcll(bg & lm); if (pos < 256u) dst[pos] = (unsigned short)e; }
;       if (ise) { const unsigned rr = oe + __popcll(be & lm); if (rr < 256u) candi[rr] = (unsigned)e; }
;       og += __popcll(bg); oe += __popcll(be);
;     }
.LBB0_477:
	v_readlane_b32 s0, v250, 31
	s_add_i32 s60, s0, s30
	v_ashrrev_i32_e32 v123, 31, v122
	v_lshl_add_u64 v[0:1], s[60:61], 0, v[122:123]
	v_lshlrev_b64 v[0:1], 9, v[0:1]
	v_lshl_add_u64 v[0:1], s[54:55], 0, v[0:1]
	v_cmp_lt_i32_e32 vcc, -1, v8
	v_readlane_b32 s1, v250, 32
	s_and_saveexec_b64 s[6:7], vcc
	s_cbranch_execz .LBB0_488
	v_readlane_b32 s0, v249, 18
	v_add3_u32 v10, v14, v10, s0
	v_readfirstlane_b32 s18, v8
	v_mad_u32_u24 v160, v120, 14, v10
	v_lshlrev_b32_e32 v161, 3, v120
	v_mov_b32_e32 v163, 0xff00
	s_mov_b32 s14, 0
	s_mov_b32 s15, 0
	s_mov_b32 s16, 0
.Lcp_loop:
	ds_read_b128 v[164:167], v160
	v_sub_u32_e32 v162, s18, v161
	v_add_u32_e32 v162, 1, v162
	v_med3_i32 v162, v162, 0, 8
	v_lshrrev_b32_e32 v162, v162, v163
	v_and_b32_e32 v162, 0xff, v162
	v_add_u32_e32 v174, 0xffffffe8, v161
	v_mov_b32_e32 v168, 0
	v_mov_b32_e32 v169, 0
	s_waitcnt lgkmcnt(0)
	v_and_b32_e32 v170, 0xffff, v164
	v_lshrrev_b32_e32 v171, 16, v164
	v_cmp_gt_u32_e32 vcc, v170, v9
	v_cmp_eq_u32_e64 s[0:1], v170, v9
	v_cmp_gt_u32_e64 s[4:5], v171, v9
	v_cmp_eq_u32_e64 s[10:11], v171, v9
	v_addc_co_u32_e32 v168, vcc, v168, v168, vcc
	v_addc_co_u32_e64 v169, s[0:1], v169, v169, s[0:1]
	v_addc_co_u32_e64 v168, s[4:5], v168, v168, s[4:5]
	v_addc_co_u32_e64 v169, s[10:11], v169, v169, s[10:11]
	v_and_b32_e32 v170, 0xffff, v165
	v_lshrrev_b32_e32 v171, 16, v165
	v_cmp_gt_u32_e32 vcc, v170, v9
	v_cmp_eq_u32_e64 s[0:1], v170, v9
	v_cmp_gt_u32_e64 s[4:5], v171, v9
	v_cmp_eq_u32_e64 s[10:11], v171, v9
	v_addc_co_u32_e32 v168, vcc, v168, v168, vcc
	v_addc_co_u32_e64 v169, s[0:1], v169, v169, s[0:1]
	v_addc_co_u32_e64 v168, s[4:5], v168, v168, s[4:5]
	v_addc_co_u32_e64 v169, s[10:11], v169, v169, s[10:11]
	v_and_b32_e32 v170, 0xffff, v166
	v_lshrrev_b32_e32 v171, 16, v166
	v_cmp_gt_u32_e32 vcc, v170, v9
	v_cmp_eq_u32_e64 s[0:1], v170, v9
	v_cmp_gt_u32_e64 s[4:5], v171, v9
	v_cmp_eq_u32_e64 s[10:11], v171, v9
	v_addc_co_u32_e32 v168, vcc, v168, v168, vcc
	v_addc_co_u32_e64 v169, s[0:1], v169, v169, s[0:1]
	v_addc_co_u32_e64 v168, s[4:5], v168, v168, s[4:5]
	v_addc_co_u32_e64 v169, s[10:11], v169, v169, s[10:11]
	v_and_b32_e32 v170, 0xffff, v167
	v_lshrrev_b32_e32 v171, 16, v167
	v_cmp_gt_u32_e32 vcc, v170, v9
	v_cmp_eq_u32_e64 s[0:1], v170, v9
	v_cmp_gt_u32_e64 s[4:5], v171, v9
	v_cmp_eq_u32_e64 s[10:11], v171, v9
	v_addc_co_u32_e32 v168, vcc, v168, v168, vcc
	v_addc_co_u32_e64 v169, s[0:1], v169, v169, s[0:1]
	v_addc_co_u32_e64 v168, s[4:5], v168, v168, s[4:5]
	v_addc_co_u32_e64 v169, s[10:11], v169, v169, s[10:11]
	v_and_b32_e32 v168, v168, v162
	v_and_b32_e32 v169, v169, v162
	v_bcnt_u32_b32 v178, v168, 0
	v_bcnt_u32_b32 v179, v169, 0
	v_mov_b32_e32 v180, v178
	v_mov_b32_e32 v181, v179
	s_nop 1
	v_add_u32_dpp v180, v180, v180 row_shr:1 row_mask:0xf bank_mask:0xf bound_ctrl:0
	v_add_u32_dpp v181, v181, v181 row_shr:1 row_mask:0xf bank_mask:0xf bound_ctrl:0
	s_nop 1
	v_add_u32_dpp v180, v180, v180 row_shr:2 row_mask:0xf bank_mask:0xf bound_ctrl:0
	v_add_u32_dpp v181, v181, v181 row_shr:2 row_mask:0xf bank_mask:0xf bound_ctrl:0
	s_nop 1
	v_add_u32_dpp v180, v180, v180 row_shr:4 row_mask:0xf bank_mask:0xf bound_ctrl:0
	v_add_u32_dpp v181, v181, v181 row_shr:4 row_mask:0xf bank_mask:0xf bound_ctrl:0
	s_nop 1
	v_add_u32_dpp v180, v180, v180 row_shr:8 row_mask:0xf bank_mask:0xf bound_ctrl:0
	v_add_u32_dpp v181, v181, v181 row_shr:8 row_mask:0xf bank_mask:0xf bound_ctrl:0
	s_nop 1
	v_add_u32_dpp v180, v180, v180 row_bcast:15 row_mask:0xa bank_mask:0xf
	v_add_u32_dpp v181, v181, v181 row_bcast:15 row_mask:0xa bank_mask:0xf
	s_nop 1
	v_add_u32_dpp v180, v180, v180 row_bcast:31 row_mask:0xc bank_mask:0xf
	v_add_u32_dpp v181, v181, v181 row_bcast:31 row_mask:0xc bank_mask:0xf
	s_nop 1
	v_readlane_b32 s4, v180, 63
	v_readlane_b32 s5, v181, 63
	v_sub_u32_e32 v180, v180, v178
	v_sub_u32_e32 v181, v181, v179
	v_add_u32_e32 v182, s16, v180
	v_add_u32_e32 v183, s15, v181
	s_cmp_eq_u32 s4, 0
	s_cbranch_scc1 .Lcp_gdone
	s_mov_b64 s[12:13], exec
.Lcp_gloop:
	v_cmp_ne_u32_e32 vcc, 0, v168
	s_and_b64 exec, s[12:13], vcc
	s_cbranch_execz .Lcp_gend
	v_ffbh_u32_e32 v172, v168
	v_mov_b32_e32 v192, v182
	v_sub_u32_e32 v173, 31, v172
	v_add_u32_e32 v172, v172, v174
	v_lshlrev_b32_e32 v173, v173, v221
	v_lshl_add_u64 v[176:177], v[192:193], 1, v[0:1]
	v_xor_b32_e32 v168, v168, v173
	global_store_short v[176:177], v172, off
	v_add_u32_e32 v182, 1, v182
	s_branch .Lcp_gloop
.Lcp_gend:
	s_mov_b64 exec, s[12:13]
.Lcp_gdone:
	s_cmp_eq_u32 s5, 0
	s_cbranch_scc1 .Lcp_edone
	s_mov_b64 s[12:13], exec
.Lcp_eloop:
	v_cmp_ne_u32_e32 vcc, 0, v169
	s_and_b64 exec, s[12:13], vcc
	s_cbranch_execz .Lcp_eend
	v_ffbh_u32_e32 v172, v169
	v_cmp_gt_u32_e32 vcc, 0x100, v183
	v_sub_u32_e32 v173, 31, v172
	v_add_u32_e32 v172, v172, v174
	v_lshlrev_b32_e32 v173, v173, v221
	v_lshl_add_u32 v175, v183, 2, v4
	v_xor_b32_e32 v169, v169, v173
	v_add_u32_e32 v183, 1, v183
	s_and_saveexec_b64 s[10:11], vcc
	ds_write_b32 v175, v172 offset:4096
	s_or_b64 exec, exec, s[10:11]
	s_branch .Lcp_eloop

; DI void select_item(const P& p, int b, int quad4, int bid, char* smem, const SelPre& pre) {
;     ...
;     for (int base = 0; base < n; base += 64) {
;       const int e = base + lane;
;       const unsigned u = e < n ? (unsigned)s[e] : 0u;
;       const bool isg = e < n && u > thr, ise = e < n && u == thr;
;       const unsigned long long bg = __ballot(isg), be = __ballot(ise);
;       if (isg) { const unsigned pos = og + __popcll(bg & lm); if (pos < 256u) dst[pos] = (unsigned short)e; }
;       if (ise) { const unsigned rr = oe + __popcll(be & lm); if (rr < 256u) candi[rr] = (unsigned)e; }
;       og += __popcll(bg); oe += __popcll(be);
;     }
.Lcp_edone:
	s_add_i32 s16, s16, s4
	s_add_i32 s15, s15, s5
	s_addk_i32 s14, 0x200
	v_add_u32_e32 v160, 0x400, v160
	v_add_u32_e32 v161, 0x200, v161
	s_cmp_le_i32 s14, s18
	s_cbranch_scc1 .Lcp_loop
